# z + K-loop LDS read addresses hoisted to per-unit VGPRs and SALU-only skip flag (4 fewer VALU per K trip)
# speedup vs baseline: 1.0201x; 1.0050x over previous
.LBB0_246:
	s_ashr_i32 s19, s18, 31
	s_lshl_b64 s[26:27], s[18:19], 19
	s_add_u32 s26, s54, s26
	s_addc_u32 s27, s55, s27
	s_and_b64 s[28:29], s[4:5], exec
	s_cselect_b32 s19, s27, s35
	s_cselect_b32 s85, s26, s34
	s_ashr_i32 s17, s16, 31
	s_lshl_b64 s[28:29], s[16:17], 19
	s_add_u32 s28, s21, s28
	s_addc_u32 s29, s25, s29
	s_and_b64 s[58:59], s[4:5], exec
	s_cselect_b32 s17, s29, s53
	s_cselect_b32 s88, s28, s52
	s_cmp_lg_u32 s36, 0
	s_cselect_b64 s[36:37], -1, 0
	s_add_u32 s91, s52, 0x100
	v_mov_b64_e32 v[0:1], 0
	v_lshl_add_u64 v[146:147], s[34:35], 0, v[138:139]
	v_lshl_add_u64 v[148:149], s[34:35], 0, v[140:141]
	s_addc_u32 s92, s53, 0
	s_mov_b32 s93, -2
	s_mov_b64 s[52:53], 0
	v_mov_b64_e32 v[2:3], 0
	v_mov_b64_e32 v[4:5], 0
	v_mov_b64_e32 v[6:7], 0
	v_mov_b64_e32 v[16:17], 0
	v_mov_b64_e32 v[18:19], 0
	v_mov_b64_e32 v[20:21], 0
	v_mov_b64_e32 v[22:23], 0
	v_mov_b64_e32 v[32:33], 0
	v_mov_b64_e32 v[34:35], 0
	v_mov_b64_e32 v[36:37], 0
	v_mov_b64_e32 v[38:39], 0
	v_mov_b64_e32 v[48:49], 0
	v_mov_b64_e32 v[50:51], 0
	v_mov_b64_e32 v[52:53], 0
	v_mov_b64_e32 v[54:55], 0
	v_mov_b64_e32 v[8:9], 0
	v_mov_b64_e32 v[10:11], 0
	v_mov_b64_e32 v[12:13], 0
	v_mov_b64_e32 v[14:15], 0
	v_mov_b64_e32 v[24:25], 0
	v_mov_b64_e32 v[26:27], 0
	v_mov_b64_e32 v[28:29], 0
	v_mov_b64_e32 v[30:31], 0
	v_mov_b64_e32 v[40:41], 0
	v_mov_b64_e32 v[42:43], 0
	v_mov_b64_e32 v[44:45], 0
	v_mov_b64_e32 v[46:47], 0
	v_mov_b64_e32 v[56:57], 0
	v_mov_b64_e32 v[58:59], 0
	v_mov_b64_e32 v[60:61], 0
	v_mov_b64_e32 v[62:63], 0
	v_mov_b64_e32 v[64:65], 0
	v_mov_b64_e32 v[66:67], 0
	v_mov_b64_e32 v[68:69], 0
	v_mov_b64_e32 v[70:71], 0
	v_mov_b64_e32 v[80:81], 0
	v_mov_b64_e32 v[82:83], 0
	v_mov_b64_e32 v[84:85], 0
	v_mov_b64_e32 v[86:87], 0
	v_mov_b64_e32 v[96:97], 0
	v_mov_b64_e32 v[98:99], 0
	v_mov_b64_e32 v[100:101], 0
	v_mov_b64_e32 v[102:103], 0
	v_mov_b64_e32 v[112:113], 0
	v_mov_b64_e32 v[114:115], 0
	v_mov_b64_e32 v[116:117], 0
	v_mov_b64_e32 v[118:119], 0
	v_mov_b64_e32 v[72:73], 0
	v_mov_b64_e32 v[74:75], 0
	v_mov_b64_e32 v[76:77], 0
	v_mov_b64_e32 v[78:79], 0
	v_mov_b64_e32 v[88:89], 0
	v_mov_b64_e32 v[90:91], 0
	v_mov_b64_e32 v[92:93], 0
	v_mov_b64_e32 v[94:95], 0
	v_mov_b64_e32 v[104:105], 0
	v_mov_b64_e32 v[106:107], 0
	v_mov_b64_e32 v[108:109], 0
	v_mov_b64_e32 v[110:111], 0
	v_mov_b64_e32 v[120:121], 0
	v_mov_b64_e32 v[122:123], 0
	v_mov_b64_e32 v[124:125], 0
	v_mov_b64_e32 v[126:127], 0
	v_add_u32_e32 v253, 0x18000, v150
	v_add_u32_e32 v254, 0x1c000, v150
.LBB0_247:
	s_add_u32 s98, s34, s52
	s_addc_u32 s99, s35, s53
	s_add_u32 s33, s34, s52
	s_addc_u32 s58, s35, s53
	s_add_u32 s33, s33, 0x100
	s_addc_u32 s60, s58, 0
	ds_read_b128 v[156:159], v152
	ds_read_b128 v[160:163], v152 offset:1024
	ds_read_b128 v[164:167], v152 offset:2048
	ds_read_b128 v[168:171], v152 offset:3072
	ds_read_b128 v[172:175], v153
	ds_read_b128 v[176:179], v153 offset:1024
	ds_read_b128 v[180:183], v153 offset:2048
	ds_read_b128 v[184:187], v153 offset:3072
	s_add_u32 s94, s91, s52
	s_addc_u32 s95, s92, s53
	s_cmp_eq_u32 s52, 0
	s_cselect_b64 s[58:59], -1, 0
	s_and_b64 s[58:59], s[36:37], s[58:59]
	s_cselect_b32 s32, 1, 0
	s_cmpk_eq_i32 s52, 0x700
	s_cselect_b32 s61, s19, s60
	s_cselect_b32 s60, s85, s33
	s_mov_b32 s33, s32
	s_cselect_b32 s59, s17, s95
	s_cselect_b32 s58, s88, s94
	s_add_i32 m0, s31, 0xc000
	ds_read_b128 v[188:191], v154
	ds_read_b128 v[192:195], v154 offset:1024
	ds_read_b128 v[196:199], v154 offset:2048
	ds_read_b128 v[200:203], v154 offset:3072
	ds_read_b128 v[204:207], v154 offset:4096
	ds_read_b128 v[212:215], v154 offset:5120
	ds_read_b128 v[216:219], v154 offset:6144
	ds_read_b128 v[220:223], v154 offset:7168
	global_load_lds_dwordx4 v138, s[98:99]
	s_add_i32 m0, s31, 0xe000
	s_and_b32 s33, s33, 1
	global_load_lds_dwordx4 v140, s[98:99]
	s_cmp_lg_u32 s33, 0
	s_cbranch_scc1 .Lpg8skip0
	s_waitcnt vmcnt(8)

.Lpg8skip1:
	s_waitcnt lgkmcnt(0)
	s_barrier
	s_setprio 1
	s_waitcnt lgkmcnt(0)
	v_mfma_f32_16x16x32_bf16 v[60:63], v[156:159], v[188:191], v[60:63]
	v_mfma_f32_16x16x32_bf16 v[56:59], v[164:167], v[188:191], v[56:59]
	v_mfma_f32_16x16x32_bf16 v[44:47], v[156:159], v[196:199], v[44:47]
	v_mfma_f32_16x16x32_bf16 v[40:43], v[164:167], v[196:199], v[40:43]
	v_mfma_f32_16x16x32_bf16 v[28:31], v[156:159], v[204:207], v[28:31]
	v_mfma_f32_16x16x32_bf16 v[24:27], v[164:167], v[204:207], v[24:27]
	v_mfma_f32_16x16x32_bf16 v[12:15], v[156:159], v[216:219], v[12:15]
	v_mfma_f32_16x16x32_bf16 v[8:11], v[164:167], v[216:219], v[8:11]
	v_mfma_f32_16x16x32_bf16 v[60:63], v[160:163], v[192:195], v[60:63]
	v_mfma_f32_16x16x32_bf16 v[56:59], v[168:171], v[192:195], v[56:59]
	v_mfma_f32_16x16x32_bf16 v[44:47], v[160:163], v[200:203], v[44:47]
	v_mfma_f32_16x16x32_bf16 v[40:43], v[168:171], v[200:203], v[40:43]
	v_mfma_f32_16x16x32_bf16 v[28:31], v[160:163], v[212:215], v[28:31]
	v_mfma_f32_16x16x32_bf16 v[24:27], v[168:171], v[212:215], v[24:27]
	v_mfma_f32_16x16x32_bf16 v[12:15], v[160:163], v[220:223], v[12:15]
	v_mfma_f32_16x16x32_bf16 v[8:11], v[168:171], v[220:223], v[8:11]
	s_setprio 0
	s_setprio 1
	v_mfma_f32_16x16x32_bf16 v[52:55], v[172:175], v[188:191], v[52:55]
	v_mfma_f32_16x16x32_bf16 v[48:51], v[180:183], v[188:191], v[48:51]
	v_mfma_f32_16x16x32_bf16 v[36:39], v[172:175], v[196:199], v[36:39]
	v_mfma_f32_16x16x32_bf16 v[32:35], v[180:183], v[196:199], v[32:35]
	v_mfma_f32_16x16x32_bf16 v[20:23], v[172:175], v[204:207], v[20:23]
	v_mfma_f32_16x16x32_bf16 v[16:19], v[180:183], v[204:207], v[16:19]
	v_mfma_f32_16x16x32_bf16 v[4:7], v[172:175], v[216:219], v[4:7]
	v_mfma_f32_16x16x32_bf16 v[0:3], v[180:183], v[216:219], v[0:3]
	v_mfma_f32_16x16x32_bf16 v[52:55], v[176:179], v[192:195], v[52:55]
	v_mfma_f32_16x16x32_bf16 v[48:51], v[184:187], v[192:195], v[48:51]
	v_mfma_f32_16x16x32_bf16 v[36:39], v[176:179], v[200:203], v[36:39]
	v_mfma_f32_16x16x32_bf16 v[32:35], v[184:187], v[200:203], v[32:35]
	v_mfma_f32_16x16x32_bf16 v[20:23], v[176:179], v[212:215], v[20:23]
	v_mfma_f32_16x16x32_bf16 v[16:19], v[184:187], v[212:215], v[16:19]
	v_mfma_f32_16x16x32_bf16 v[4:7], v[176:179], v[220:223], v[4:7]
	v_mfma_f32_16x16x32_bf16 v[0:3], v[184:187], v[220:223], v[0:3]
	s_setprio 0
	s_barrier
	s_add_i32 s33, 0, 0x18000
	s_add_i32 s94, 0, 0x1c000
	ds_read_b128 v[156:159], v253
	ds_read_b128 v[160:163], v253 offset:1024
	ds_read_b128 v[164:167], v253 offset:2048
	ds_read_b128 v[168:171], v253 offset:3072
	ds_read_b128 v[172:175], v254
	ds_read_b128 v[176:179], v254 offset:1024
	ds_read_b128 v[180:183], v254 offset:2048
	ds_read_b128 v[184:187], v254 offset:3072
	s_add_u32 s60, s60, 0x40000
	s_addc_u32 s61, s61, 0
	s_mov_b32 m0, s69
	ds_read_b128 v[188:191], v154 offset:32768
	ds_read_b128 v[192:195], v154 offset:33792
	ds_read_b128 v[196:199], v154 offset:34816
	ds_read_b128 v[200:203], v154 offset:35840
	ds_read_b128 v[204:207], v154 offset:36864
	ds_read_b128 v[212:215], v154 offset:37888
	ds_read_b128 v[216:219], v154 offset:38912
	ds_read_b128 v[220:223], v154 offset:39936
	global_load_lds_dwordx4 v134, s[60:61]
	s_mov_b32 m0, s70
	s_nop 0
	global_load_lds_dwordx4 v130, s[60:61]
	s_waitcnt vmcnt(8)
	s_waitcnt lgkmcnt(0)
	s_barrier
	s_setprio 1
	s_waitcnt lgkmcnt(0)
	v_mfma_f32_16x16x32_bf16 v[124:127], v[156:159], v[188:191], v[124:127]
	v_mfma_f32_16x16x32_bf16 v[120:123], v[164:167], v[188:191], v[120:123]
	v_mfma_f32_16x16x32_bf16 v[108:111], v[156:159], v[196:199], v[108:111]
	v_mfma_f32_16x16x32_bf16 v[104:107], v[164:167], v[196:199], v[104:107]
	v_mfma_f32_16x16x32_bf16 v[92:95], v[156:159], v[204:207], v[92:95]
	v_mfma_f32_16x16x32_bf16 v[88:91], v[164:167], v[204:207], v[88:91]
	v_mfma_f32_16x16x32_bf16 v[76:79], v[156:159], v[216:219], v[76:79]
	v_mfma_f32_16x16x32_bf16 v[72:75], v[164:167], v[216:219], v[72:75]
	v_mfma_f32_16x16x32_bf16 v[124:127], v[160:163], v[192:195], v[124:127]
	v_mfma_f32_16x16x32_bf16 v[120:123], v[168:171], v[192:195], v[120:123]
	v_mfma_f32_16x16x32_bf16 v[108:111], v[160:163], v[200:203], v[108:111]
	v_mfma_f32_16x16x32_bf16 v[104:107], v[168:171], v[200:203], v[104:107]
	v_mfma_f32_16x16x32_bf16 v[92:95], v[160:163], v[212:215], v[92:95]
	v_mfma_f32_16x16x32_bf16 v[88:91], v[168:171], v[212:215], v[88:91]
	v_mfma_f32_16x16x32_bf16 v[76:79], v[160:163], v[220:223], v[76:79]
	v_mfma_f32_16x16x32_bf16 v[72:75], v[168:171], v[220:223], v[72:75]
	s_setprio 0
	s_setprio 1
	v_mfma_f32_16x16x32_bf16 v[116:119], v[172:175], v[188:191], v[116:119]
	v_mfma_f32_16x16x32_bf16 v[112:115], v[180:183], v[188:191], v[112:115]
	v_mfma_f32_16x16x32_bf16 v[100:103], v[172:175], v[196:199], v[100:103]
	v_mfma_f32_16x16x32_bf16 v[96:99], v[180:183], v[196:199], v[96:99]
	v_mfma_f32_16x16x32_bf16 v[84:87], v[172:175], v[204:207], v[84:87]
	v_mfma_f32_16x16x32_bf16 v[80:83], v[180:183], v[204:207], v[80:83]
	v_mfma_f32_16x16x32_bf16 v[68:71], v[172:175], v[216:219], v[68:71]
	v_mfma_f32_16x16x32_bf16 v[64:67], v[180:183], v[216:219], v[64:67]
	v_mfma_f32_16x16x32_bf16 v[116:119], v[176:179], v[192:195], v[116:119]
	v_mfma_f32_16x16x32_bf16 v[112:115], v[184:187], v[192:195], v[112:115]
	v_mfma_f32_16x16x32_bf16 v[100:103], v[176:179], v[200:203], v[100:103]
	v_mfma_f32_16x16x32_bf16 v[96:99], v[184:187], v[200:203], v[96:99]
	v_mfma_f32_16x16x32_bf16 v[84:87], v[176:179], v[212:215], v[84:87]
	v_mfma_f32_16x16x32_bf16 v[80:83], v[184:187], v[212:215], v[80:83]
	v_mfma_f32_16x16x32_bf16 v[68:71], v[176:179], v[220:223], v[68:71]
	v_mfma_f32_16x16x32_bf16 v[64:67], v[184:187], v[220:223], v[64:67]
	s_setprio 0
	s_barrier
	s_add_i32 s33, s33, s48
	s_mov_b32 m0, s33
	ds_read_b128 v[188:191], v154 offset:49152
	ds_read_b128 v[192:195], v154 offset:50176
	ds_read_b128 v[196:199], v154 offset:51200
	ds_read_b128 v[200:203], v154 offset:52224
	ds_read_b128 v[204:207], v154 offset:53248
	ds_read_b128 v[212:215], v154 offset:54272
	ds_read_b128 v[216:219], v154 offset:55296
	ds_read_b128 v[220:223], v154 offset:56320
	global_load_lds_dwordx4 v132, s[98:99]
	s_add_i32 m0, s33, 0x2000
	s_add_u32 s58, s58, 0x40080
	s_addc_u32 s59, s59, 0
	s_add_i32 s33, s94, s48
	global_load_lds_dwordx4 v128, s[98:99]
	s_mov_b32 m0, s33
	s_nop 0
	global_load_lds_dwordx4 v132, s[58:59]
	s_add_i32 m0, s33, 0x2000
	s_nop 0
	global_load_lds_dwordx4 v128, s[58:59]
	s_mov_b32 m0, s71
	s_nop 0
	global_load_lds_dwordx4 v134, s[100:101]
	s_mov_b32 m0, s72
	s_nop 0
	global_load_lds_dwordx4 v130, s[100:101]
	s_waitcnt vmcnt(8)
	s_waitcnt lgkmcnt(0)
	s_barrier
	s_setprio 1
	s_waitcnt lgkmcnt(0)
	v_mfma_f32_16x16x32_bf16 v[60:63], v[156:159], v[188:191], v[60:63]
	v_mfma_f32_16x16x32_bf16 v[56:59], v[164:167], v[188:191], v[56:59]
	v_mfma_f32_16x16x32_bf16 v[44:47], v[156:159], v[196:199], v[44:47]
	v_mfma_f32_16x16x32_bf16 v[40:43], v[164:167], v[196:199], v[40:43]
	v_mfma_f32_16x16x32_bf16 v[28:31], v[156:159], v[204:207], v[28:31]
	v_mfma_f32_16x16x32_bf16 v[24:27], v[164:167], v[204:207], v[24:27]
	v_mfma_f32_16x16x32_bf16 v[12:15], v[156:159], v[216:219], v[12:15]
	v_mfma_f32_16x16x32_bf16 v[8:11], v[164:167], v[216:219], v[8:11]
	v_mfma_f32_16x16x32_bf16 v[60:63], v[160:163], v[192:195], v[60:63]
	v_mfma_f32_16x16x32_bf16 v[56:59], v[168:171], v[192:195], v[56:59]
	v_mfma_f32_16x16x32_bf16 v[44:47], v[160:163], v[200:203], v[44:47]
	v_mfma_f32_16x16x32_bf16 v[40:43], v[168:171], v[200:203], v[40:43]
	v_mfma_f32_16x16x32_bf16 v[28:31], v[160:163], v[212:215], v[28:31]
	v_mfma_f32_16x16x32_bf16 v[24:27], v[168:171], v[212:215], v[24:27]
	v_mfma_f32_16x16x32_bf16 v[12:15], v[160:163], v[220:223], v[12:15]
	v_mfma_f32_16x16x32_bf16 v[8:11], v[168:171], v[220:223], v[8:11]
	s_setprio 0
	s_setprio 1
	v_mfma_f32_16x16x32_bf16 v[52:55], v[172:175], v[188:191], v[52:55]
	v_mfma_f32_16x16x32_bf16 v[48:51], v[180:183], v[188:191], v[48:51]
	v_mfma_f32_16x16x32_bf16 v[36:39], v[172:175], v[196:199], v[36:39]
	v_mfma_f32_16x16x32_bf16 v[32:35], v[180:183], v[196:199], v[32:35]
	v_mfma_f32_16x16x32_bf16 v[20:23], v[172:175], v[204:207], v[20:23]
	v_mfma_f32_16x16x32_bf16 v[16:19], v[180:183], v[204:207], v[16:19]
	v_mfma_f32_16x16x32_bf16 v[4:7], v[172:175], v[216:219], v[4:7]
	v_mfma_f32_16x16x32_bf16 v[0:3], v[180:183], v[216:219], v[0:3]
	v_mfma_f32_16x16x32_bf16 v[52:55], v[176:179], v[192:195], v[52:55]
	v_mfma_f32_16x16x32_bf16 v[48:51], v[184:187], v[192:195], v[48:51]
	v_mfma_f32_16x16x32_bf16 v[36:39], v[176:179], v[200:203], v[36:39]
	v_mfma_f32_16x16x32_bf16 v[32:35], v[184:187], v[200:203], v[32:35]
	v_mfma_f32_16x16x32_bf16 v[20:23], v[176:179], v[212:215], v[20:23]
	v_mfma_f32_16x16x32_bf16 v[16:19], v[184:187], v[212:215], v[16:19]
	v_mfma_f32_16x16x32_bf16 v[4:7], v[176:179], v[220:223], v[4:7]
	v_mfma_f32_16x16x32_bf16 v[0:3], v[184:187], v[220:223], v[0:3]
	s_setprio 0
	s_barrier
	s_add_i32 s93, s93, 2
	s_add_u32 s52, s52, 0x100
	s_addc_u32 s53, s53, 0
	s_cmp_gt_u32 s93, 13
	s_cbranch_scc0 .LBB0_247
	s_and_b64 vcc, exec, s[14:15]
	s_cbranch_vccz .LBB0_250
	s_barrier

.LBB0_323:
	s_add_u32 s78, s28, 0x100
	v_mov_b64_e32 v[0:1], 0
	s_addc_u32 s79, s29, 0
	s_mov_b32 s80, -2
	v_mov_b64_e32 v[2:3], 0
	v_mov_b64_e32 v[4:5], 0
	v_mov_b64_e32 v[6:7], 0
	v_mov_b64_e32 v[8:9], 0
	v_mov_b64_e32 v[10:11], 0
	v_mov_b64_e32 v[20:21], 0
	v_mov_b64_e32 v[22:23], 0
	v_mov_b64_e32 v[24:25], 0
	v_mov_b64_e32 v[26:27], 0
	v_mov_b64_e32 v[36:37], 0
	v_mov_b64_e32 v[38:39], 0
	v_mov_b64_e32 v[40:41], 0
	v_mov_b64_e32 v[42:43], 0
	v_mov_b64_e32 v[52:53], 0
	v_mov_b64_e32 v[54:55], 0
	v_mov_b64_e32 v[12:13], 0
	v_mov_b64_e32 v[14:15], 0
	v_mov_b64_e32 v[16:17], 0
	v_mov_b64_e32 v[18:19], 0
	v_mov_b64_e32 v[28:29], 0
	v_mov_b64_e32 v[30:31], 0
	v_mov_b64_e32 v[32:33], 0
	v_mov_b64_e32 v[34:35], 0
	v_mov_b64_e32 v[44:45], 0
	v_mov_b64_e32 v[46:47], 0
	v_mov_b64_e32 v[48:49], 0
	v_mov_b64_e32 v[50:51], 0
	v_mov_b64_e32 v[56:57], 0
	v_mov_b64_e32 v[58:59], 0
	v_mov_b64_e32 v[60:61], 0
	v_mov_b64_e32 v[62:63], 0
	v_mov_b64_e32 v[64:65], 0
	v_mov_b64_e32 v[66:67], 0
	v_mov_b64_e32 v[68:69], 0
	v_mov_b64_e32 v[70:71], 0
	v_mov_b64_e32 v[72:73], 0
	v_mov_b64_e32 v[74:75], 0
	v_mov_b64_e32 v[84:85], 0
	v_mov_b64_e32 v[86:87], 0
	v_mov_b64_e32 v[88:89], 0
	v_mov_b64_e32 v[90:91], 0
	v_mov_b64_e32 v[100:101], 0
	v_mov_b64_e32 v[102:103], 0
	v_mov_b64_e32 v[104:105], 0
	v_mov_b64_e32 v[106:107], 0
	v_mov_b64_e32 v[116:117], 0
	v_mov_b64_e32 v[118:119], 0
	v_mov_b64_e32 v[76:77], 0
	v_mov_b64_e32 v[78:79], 0
	v_mov_b64_e32 v[80:81], 0
	v_mov_b64_e32 v[82:83], 0
	v_mov_b64_e32 v[92:93], 0
	v_mov_b64_e32 v[94:95], 0
	v_mov_b64_e32 v[96:97], 0
	v_mov_b64_e32 v[98:99], 0
	v_mov_b64_e32 v[108:109], 0
	v_mov_b64_e32 v[110:111], 0
	v_mov_b64_e32 v[112:113], 0
	v_mov_b64_e32 v[114:115], 0
	v_mov_b64_e32 v[120:121], 0
	v_mov_b64_e32 v[122:123], 0
	v_mov_b64_e32 v[124:125], 0
	v_mov_b64_e32 v[126:127], 0
	v_add_u32_e32 v253, 0x18000, v153
	v_add_u32_e32 v254, 0x1c000, v153

.Lpg8skip3:
	s_waitcnt lgkmcnt(0)
	s_barrier
	s_setprio 1
	s_waitcnt lgkmcnt(0)
	v_mfma_f32_16x16x32_bf16 v[60:63], v[144:147], v[182:185], v[60:63]
	v_mfma_f32_16x16x32_bf16 v[56:59], v[158:161], v[182:185], v[56:59]
	v_mfma_f32_16x16x32_bf16 v[48:51], v[144:147], v[190:193], v[48:51]
	v_mfma_f32_16x16x32_bf16 v[44:47], v[158:161], v[190:193], v[44:47]
	v_mfma_f32_16x16x32_bf16 v[32:35], v[144:147], v[198:201], v[32:35]
	v_mfma_f32_16x16x32_bf16 v[28:31], v[158:161], v[198:201], v[28:31]
	v_mfma_f32_16x16x32_bf16 v[16:19], v[144:147], v[212:215], v[16:19]
	v_mfma_f32_16x16x32_bf16 v[12:15], v[158:161], v[212:215], v[12:15]
	v_mfma_f32_16x16x32_bf16 v[60:63], v[148:151], v[186:189], v[60:63]
	v_mfma_f32_16x16x32_bf16 v[56:59], v[162:165], v[186:189], v[56:59]
	v_mfma_f32_16x16x32_bf16 v[48:51], v[148:151], v[194:197], v[48:51]
	v_mfma_f32_16x16x32_bf16 v[44:47], v[162:165], v[194:197], v[44:47]
	v_mfma_f32_16x16x32_bf16 v[32:35], v[148:151], v[202:205], v[32:35]
	v_mfma_f32_16x16x32_bf16 v[28:31], v[162:165], v[202:205], v[28:31]
	v_mfma_f32_16x16x32_bf16 v[16:19], v[148:151], v[216:219], v[16:19]
	v_mfma_f32_16x16x32_bf16 v[12:15], v[162:165], v[216:219], v[12:15]
	s_setprio 0
	s_setprio 1
	v_mfma_f32_16x16x32_bf16 v[52:55], v[166:169], v[182:185], v[52:55]
	v_mfma_f32_16x16x32_bf16 v[40:43], v[174:177], v[182:185], v[40:43]
	v_mfma_f32_16x16x32_bf16 v[36:39], v[166:169], v[190:193], v[36:39]
	v_mfma_f32_16x16x32_bf16 v[24:27], v[174:177], v[190:193], v[24:27]
	v_mfma_f32_16x16x32_bf16 v[20:23], v[166:169], v[198:201], v[20:23]
	v_mfma_f32_16x16x32_bf16 v[8:11], v[174:177], v[198:201], v[8:11]
	v_mfma_f32_16x16x32_bf16 v[4:7], v[166:169], v[212:215], v[4:7]
	v_mfma_f32_16x16x32_bf16 v[0:3], v[174:177], v[212:215], v[0:3]
	v_mfma_f32_16x16x32_bf16 v[52:55], v[170:173], v[186:189], v[52:55]
	v_mfma_f32_16x16x32_bf16 v[40:43], v[178:181], v[186:189], v[40:43]
	v_mfma_f32_16x16x32_bf16 v[36:39], v[170:173], v[194:197], v[36:39]
	v_mfma_f32_16x16x32_bf16 v[24:27], v[178:181], v[194:197], v[24:27]
	v_mfma_f32_16x16x32_bf16 v[20:23], v[170:173], v[202:205], v[20:23]
	v_mfma_f32_16x16x32_bf16 v[8:11], v[178:181], v[202:205], v[8:11]
	v_mfma_f32_16x16x32_bf16 v[4:7], v[170:173], v[216:219], v[4:7]
	v_mfma_f32_16x16x32_bf16 v[0:3], v[178:181], v[216:219], v[0:3]
	s_setprio 0
	s_barrier
	s_add_i32 s33, 0, 0x18000
	s_add_i32 s81, 0, 0x1c000
	ds_read_b128 v[144:147], v253
	ds_read_b128 v[148:151], v253 offset:1024
	ds_read_b128 v[158:161], v253 offset:2048
	ds_read_b128 v[162:165], v253 offset:3072
	ds_read_b128 v[166:169], v254
	ds_read_b128 v[170:173], v254 offset:1024
	ds_read_b128 v[174:177], v254 offset:2048
	ds_read_b128 v[178:181], v254 offset:3072
	s_add_u32 s26, s34, 0xb0000
	s_addc_u32 s27, s35, 0
	s_mov_b32 m0, s49
	ds_read_b128 v[182:185], v157 offset:32768
	ds_read_b128 v[186:189], v157 offset:33792
	ds_read_b128 v[190:193], v157 offset:34816
	ds_read_b128 v[194:197], v157 offset:35840
	ds_read_b128 v[198:201], v157 offset:36864
	ds_read_b128 v[202:205], v157 offset:37888
	ds_read_b128 v[212:215], v157 offset:38912
	ds_read_b128 v[216:219], v157 offset:39936
	global_load_lds_dwordx4 v134, s[26:27]
	s_mov_b32 m0, s52
	s_nop 0
	global_load_lds_dwordx4 v130, s[26:27]
	s_waitcnt vmcnt(8)
	s_waitcnt lgkmcnt(0)
	s_barrier
	s_setprio 1
	s_waitcnt lgkmcnt(0)
	v_mfma_f32_16x16x32_bf16 v[124:127], v[144:147], v[182:185], v[124:127]
	v_mfma_f32_16x16x32_bf16 v[120:123], v[158:161], v[182:185], v[120:123]
	v_mfma_f32_16x16x32_bf16 v[112:115], v[144:147], v[190:193], v[112:115]
	v_mfma_f32_16x16x32_bf16 v[108:111], v[158:161], v[190:193], v[108:111]
	v_mfma_f32_16x16x32_bf16 v[96:99], v[144:147], v[198:201], v[96:99]
	v_mfma_f32_16x16x32_bf16 v[92:95], v[158:161], v[198:201], v[92:95]
	v_mfma_f32_16x16x32_bf16 v[80:83], v[144:147], v[212:215], v[80:83]
	v_mfma_f32_16x16x32_bf16 v[76:79], v[158:161], v[212:215], v[76:79]
	v_mfma_f32_16x16x32_bf16 v[124:127], v[148:151], v[186:189], v[124:127]
	v_mfma_f32_16x16x32_bf16 v[120:123], v[162:165], v[186:189], v[120:123]
	v_mfma_f32_16x16x32_bf16 v[112:115], v[148:151], v[194:197], v[112:115]
	v_mfma_f32_16x16x32_bf16 v[108:111], v[162:165], v[194:197], v[108:111]
	v_mfma_f32_16x16x32_bf16 v[96:99], v[148:151], v[202:205], v[96:99]
	v_mfma_f32_16x16x32_bf16 v[92:95], v[162:165], v[202:205], v[92:95]
	v_mfma_f32_16x16x32_bf16 v[80:83], v[148:151], v[216:219], v[80:83]
	v_mfma_f32_16x16x32_bf16 v[76:79], v[162:165], v[216:219], v[76:79]
	s_setprio 0
	s_setprio 1
	v_mfma_f32_16x16x32_bf16 v[116:119], v[166:169], v[182:185], v[116:119]
	v_mfma_f32_16x16x32_bf16 v[104:107], v[174:177], v[182:185], v[104:107]
	v_mfma_f32_16x16x32_bf16 v[100:103], v[166:169], v[190:193], v[100:103]
	v_mfma_f32_16x16x32_bf16 v[88:91], v[174:177], v[190:193], v[88:91]
	v_mfma_f32_16x16x32_bf16 v[84:87], v[166:169], v[198:201], v[84:87]
	v_mfma_f32_16x16x32_bf16 v[72:75], v[174:177], v[198:201], v[72:75]
	v_mfma_f32_16x16x32_bf16 v[68:71], v[166:169], v[212:215], v[68:71]
	v_mfma_f32_16x16x32_bf16 v[64:67], v[174:177], v[212:215], v[64:67]
	v_mfma_f32_16x16x32_bf16 v[116:119], v[170:173], v[186:189], v[116:119]
	v_mfma_f32_16x16x32_bf16 v[104:107], v[178:181], v[186:189], v[104:107]
	v_mfma_f32_16x16x32_bf16 v[100:103], v[170:173], v[194:197], v[100:103]
	v_mfma_f32_16x16x32_bf16 v[88:91], v[178:181], v[194:197], v[88:91]
	v_mfma_f32_16x16x32_bf16 v[84:87], v[170:173], v[202:205], v[84:87]
	v_mfma_f32_16x16x32_bf16 v[72:75], v[178:181], v[202:205], v[72:75]
	v_mfma_f32_16x16x32_bf16 v[68:71], v[170:173], v[216:219], v[68:71]
	v_mfma_f32_16x16x32_bf16 v[64:67], v[178:181], v[216:219], v[64:67]
	s_setprio 0
	s_barrier
	s_add_i32 s26, s33, s36
	s_mov_b32 m0, s26
	ds_read_b128 v[182:185], v157 offset:49152
	ds_read_b128 v[186:189], v157 offset:50176
	ds_read_b128 v[190:193], v157 offset:51200
	ds_read_b128 v[194:197], v157 offset:52224
	ds_read_b128 v[198:201], v157 offset:53248
	ds_read_b128 v[202:205], v157 offset:54272
	ds_read_b128 v[212:215], v157 offset:55296
	ds_read_b128 v[216:219], v157 offset:56320
	global_load_lds_dwordx4 v132, s[98:99]
	s_add_i32 m0, s26, 0x2000
	s_add_u32 s26, s30, 0xb0080
	s_addc_u32 s27, s31, 0
	s_add_i32 s30, s81, s36
	global_load_lds_dwordx4 v128, s[98:99]
	s_mov_b32 m0, s30
	s_nop 0
	global_load_lds_dwordx4 v132, s[26:27]
	s_add_i32 m0, s30, 0x2000
	s_nop 0
	global_load_lds_dwordx4 v128, s[26:27]
	s_mov_b32 m0, s60
	s_nop 0
	global_load_lds_dwordx4 v134, s[100:101]
	s_mov_b32 m0, s61
	s_nop 0
	global_load_lds_dwordx4 v130, s[100:101]
	s_waitcnt vmcnt(8)
	s_waitcnt lgkmcnt(0)
	s_barrier
	s_setprio 1
	s_waitcnt lgkmcnt(0)
	v_mfma_f32_16x16x32_bf16 v[60:63], v[144:147], v[182:185], v[60:63]
	v_mfma_f32_16x16x32_bf16 v[56:59], v[158:161], v[182:185], v[56:59]
	v_mfma_f32_16x16x32_bf16 v[48:51], v[144:147], v[190:193], v[48:51]
	v_mfma_f32_16x16x32_bf16 v[44:47], v[158:161], v[190:193], v[44:47]
	v_mfma_f32_16x16x32_bf16 v[32:35], v[144:147], v[198:201], v[32:35]
	v_mfma_f32_16x16x32_bf16 v[28:31], v[158:161], v[198:201], v[28:31]
	v_mfma_f32_16x16x32_bf16 v[16:19], v[144:147], v[212:215], v[16:19]
	v_mfma_f32_16x16x32_bf16 v[12:15], v[158:161], v[212:215], v[12:15]
	v_mfma_f32_16x16x32_bf16 v[60:63], v[148:151], v[186:189], v[60:63]
	v_mfma_f32_16x16x32_bf16 v[56:59], v[162:165], v[186:189], v[56:59]
	v_mfma_f32_16x16x32_bf16 v[48:51], v[148:151], v[194:197], v[48:51]
	v_mfma_f32_16x16x32_bf16 v[44:47], v[162:165], v[194:197], v[44:47]
	v_mfma_f32_16x16x32_bf16 v[32:35], v[148:151], v[202:205], v[32:35]
	v_mfma_f32_16x16x32_bf16 v[28:31], v[162:165], v[202:205], v[28:31]
	v_mfma_f32_16x16x32_bf16 v[16:19], v[148:151], v[216:219], v[16:19]
	v_mfma_f32_16x16x32_bf16 v[12:15], v[162:165], v[216:219], v[12:15]
	s_setprio 0
	s_setprio 1
	v_mfma_f32_16x16x32_bf16 v[52:55], v[166:169], v[182:185], v[52:55]
	v_mfma_f32_16x16x32_bf16 v[40:43], v[174:177], v[182:185], v[40:43]
	v_mfma_f32_16x16x32_bf16 v[36:39], v[166:169], v[190:193], v[36:39]
	v_mfma_f32_16x16x32_bf16 v[24:27], v[174:177], v[190:193], v[24:27]
	v_mfma_f32_16x16x32_bf16 v[20:23], v[166:169], v[198:201], v[20:23]
	v_mfma_f32_16x16x32_bf16 v[8:11], v[174:177], v[198:201], v[8:11]
	v_mfma_f32_16x16x32_bf16 v[4:7], v[166:169], v[212:215], v[4:7]
	v_mfma_f32_16x16x32_bf16 v[0:3], v[174:177], v[212:215], v[0:3]
	v_mfma_f32_16x16x32_bf16 v[52:55], v[170:173], v[186:189], v[52:55]
	v_mfma_f32_16x16x32_bf16 v[40:43], v[178:181], v[186:189], v[40:43]
	v_mfma_f32_16x16x32_bf16 v[36:39], v[170:173], v[194:197], v[36:39]
	v_mfma_f32_16x16x32_bf16 v[24:27], v[178:181], v[194:197], v[24:27]
	v_mfma_f32_16x16x32_bf16 v[20:23], v[170:173], v[202:205], v[20:23]
	v_mfma_f32_16x16x32_bf16 v[8:11], v[178:181], v[202:205], v[8:11]
	v_mfma_f32_16x16x32_bf16 v[4:7], v[170:173], v[216:219], v[4:7]
	v_mfma_f32_16x16x32_bf16 v[0:3], v[178:181], v[216:219], v[0:3]
	s_setprio 0
	s_barrier
	s_add_i32 s80, s80, 2
	s_add_u32 s78, s78, 0x100
	s_addc_u32 s79, s79, 0
	s_cmp_gt_u32 s80, 41
	s_mov_b64 s[26:27], s[28:29]
	s_cbranch_scc0 .LBB0_324
	s_and_b64 vcc, exec, s[16:17]
	s_cbranch_vccz .LBB0_327
	s_barrier

.LBB0_490:
	s_ashr_i32 s21, s20, 31
	s_lshl_b64 s[22:23], s[20:21], 19
	s_add_u32 s22, s54, s22
	s_addc_u32 s23, s55, s23
	s_and_b64 s[24:25], s[4:5], exec
	s_cselect_b32 s1, s23, s27
	s_cselect_b32 s7, s22, s26
	s_ashr_i32 s19, s18, 31
	s_lshl_b64 s[24:25], s[18:19], 19
	s_add_u32 s24, s34, s24
	s_addc_u32 s25, s35, s25
	s_and_b64 s[30:31], s[4:5], exec
	s_cselect_b32 s8, s25, s29
	s_cselect_b32 s17, s24, s28
	s_add_u32 s26, s26, 0x40080
	s_addc_u32 s27, s27, 0
	s_add_u32 s19, s28, 0x100
	v_mov_b64_e32 v[0:1], 0
	s_addc_u32 s21, s29, 0
	s_mov_b32 s68, -2
	v_mov_b64_e32 v[2:3], 0
	v_mov_b64_e32 v[4:5], 0
	v_mov_b64_e32 v[6:7], 0
	v_mov_b64_e32 v[16:17], 0
	v_mov_b64_e32 v[18:19], 0
	v_mov_b64_e32 v[20:21], 0
	v_mov_b64_e32 v[22:23], 0
	v_mov_b64_e32 v[32:33], 0
	v_mov_b64_e32 v[34:35], 0
	v_mov_b64_e32 v[36:37], 0
	v_mov_b64_e32 v[38:39], 0
	v_mov_b64_e32 v[48:49], 0
	v_mov_b64_e32 v[50:51], 0
	v_mov_b64_e32 v[52:53], 0
	v_mov_b64_e32 v[54:55], 0
	v_mov_b64_e32 v[8:9], 0
	v_mov_b64_e32 v[10:11], 0
	v_mov_b64_e32 v[12:13], 0
	v_mov_b64_e32 v[14:15], 0
	v_mov_b64_e32 v[24:25], 0
	v_mov_b64_e32 v[26:27], 0
	v_mov_b64_e32 v[28:29], 0
	v_mov_b64_e32 v[30:31], 0
	v_mov_b64_e32 v[40:41], 0
	v_mov_b64_e32 v[42:43], 0
	v_mov_b64_e32 v[44:45], 0
	v_mov_b64_e32 v[46:47], 0
	v_mov_b64_e32 v[56:57], 0
	v_mov_b64_e32 v[58:59], 0
	v_mov_b64_e32 v[60:61], 0
	v_mov_b64_e32 v[62:63], 0
	v_mov_b64_e32 v[64:65], 0
	v_mov_b64_e32 v[66:67], 0
	v_mov_b64_e32 v[68:69], 0
	v_mov_b64_e32 v[70:71], 0
	v_mov_b64_e32 v[80:81], 0
	v_mov_b64_e32 v[82:83], 0
	v_mov_b64_e32 v[84:85], 0
	v_mov_b64_e32 v[86:87], 0
	v_mov_b64_e32 v[96:97], 0
	v_mov_b64_e32 v[98:99], 0
	v_mov_b64_e32 v[100:101], 0
	v_mov_b64_e32 v[102:103], 0
	v_mov_b64_e32 v[112:113], 0
	v_mov_b64_e32 v[114:115], 0
	v_mov_b64_e32 v[116:117], 0
	v_mov_b64_e32 v[118:119], 0
	v_mov_b64_e32 v[72:73], 0
	v_mov_b64_e32 v[74:75], 0
	v_mov_b64_e32 v[76:77], 0
	v_mov_b64_e32 v[78:79], 0
	v_mov_b64_e32 v[88:89], 0
	v_mov_b64_e32 v[90:91], 0
	v_mov_b64_e32 v[92:93], 0
	v_mov_b64_e32 v[94:95], 0
	v_mov_b64_e32 v[104:105], 0
	v_mov_b64_e32 v[106:107], 0
	v_mov_b64_e32 v[108:109], 0
	v_mov_b64_e32 v[110:111], 0
	v_mov_b64_e32 v[120:121], 0
	v_mov_b64_e32 v[122:123], 0
	v_mov_b64_e32 v[124:125], 0
	v_mov_b64_e32 v[126:127], 0
	v_add_u32_e32 v253, 0x18000, v149
	v_add_u32_e32 v254, 0x1c000, v149

.Lpg8skip5:
	s_waitcnt lgkmcnt(0)
	s_barrier
	s_setprio 1
	s_waitcnt lgkmcnt(0)
	v_mfma_f32_16x16x32_bf16 v[60:63], v[128:131], v[190:193], v[60:63]
	v_mfma_f32_16x16x32_bf16 v[56:59], v[158:161], v[190:193], v[56:59]
	v_mfma_f32_16x16x32_bf16 v[44:47], v[128:131], v[198:201], v[44:47]
	v_mfma_f32_16x16x32_bf16 v[40:43], v[158:161], v[198:201], v[40:43]
	v_mfma_f32_16x16x32_bf16 v[28:31], v[128:131], v[212:215], v[28:31]
	v_mfma_f32_16x16x32_bf16 v[24:27], v[158:161], v[212:215], v[24:27]
	v_mfma_f32_16x16x32_bf16 v[12:15], v[128:131], v[220:223], v[12:15]
	v_mfma_f32_16x16x32_bf16 v[8:11], v[158:161], v[220:223], v[8:11]
	v_mfma_f32_16x16x32_bf16 v[60:63], v[132:135], v[194:197], v[60:63]
	v_mfma_f32_16x16x32_bf16 v[56:59], v[162:165], v[194:197], v[56:59]
	v_mfma_f32_16x16x32_bf16 v[44:47], v[132:135], v[202:205], v[44:47]
	v_mfma_f32_16x16x32_bf16 v[40:43], v[162:165], v[202:205], v[40:43]
	v_mfma_f32_16x16x32_bf16 v[28:31], v[132:135], v[216:219], v[28:31]
	v_mfma_f32_16x16x32_bf16 v[24:27], v[162:165], v[216:219], v[24:27]
	v_mfma_f32_16x16x32_bf16 v[12:15], v[132:135], v[224:227], v[12:15]
	v_mfma_f32_16x16x32_bf16 v[8:11], v[162:165], v[224:227], v[8:11]
	s_setprio 0
	s_setprio 1
	v_mfma_f32_16x16x32_bf16 v[52:55], v[166:169], v[190:193], v[52:55]
	v_mfma_f32_16x16x32_bf16 v[48:51], v[174:177], v[190:193], v[48:51]
	v_mfma_f32_16x16x32_bf16 v[36:39], v[166:169], v[198:201], v[36:39]
	v_mfma_f32_16x16x32_bf16 v[32:35], v[174:177], v[198:201], v[32:35]
	v_mfma_f32_16x16x32_bf16 v[20:23], v[166:169], v[212:215], v[20:23]
	v_mfma_f32_16x16x32_bf16 v[16:19], v[174:177], v[212:215], v[16:19]
	v_mfma_f32_16x16x32_bf16 v[4:7], v[166:169], v[220:223], v[4:7]
	v_mfma_f32_16x16x32_bf16 v[0:3], v[174:177], v[220:223], v[0:3]
	v_mfma_f32_16x16x32_bf16 v[52:55], v[170:173], v[194:197], v[52:55]
	v_mfma_f32_16x16x32_bf16 v[48:51], v[186:189], v[194:197], v[48:51]
	v_mfma_f32_16x16x32_bf16 v[36:39], v[170:173], v[202:205], v[36:39]
	v_mfma_f32_16x16x32_bf16 v[32:35], v[186:189], v[202:205], v[32:35]
	v_mfma_f32_16x16x32_bf16 v[20:23], v[170:173], v[216:219], v[20:23]
	v_mfma_f32_16x16x32_bf16 v[16:19], v[186:189], v[216:219], v[16:19]
	v_mfma_f32_16x16x32_bf16 v[4:7], v[170:173], v[224:227], v[4:7]
	v_mfma_f32_16x16x32_bf16 v[0:3], v[186:189], v[224:227], v[0:3]
	s_setprio 0
	s_barrier
	s_add_i32 s33, 0, 0x18000
	s_add_i32 s69, 0, 0x1c000
	ds_read_b128 v[128:131], v253
	ds_read_b128 v[132:135], v253 offset:1024
	ds_read_b128 v[158:161], v253 offset:2048
	ds_read_b128 v[162:165], v253 offset:3072
	ds_read_b128 v[166:169], v254
	ds_read_b128 v[170:173], v254 offset:1024
	ds_read_b128 v[174:177], v254 offset:2048
	ds_read_b128 v[186:189], v254 offset:3072
	s_add_u32 s30, s30, 0x40000
	s_addc_u32 s31, s31, 0
	s_mov_b32 m0, s43
	ds_read_b128 v[190:193], v180 offset:32768
	ds_read_b128 v[194:197], v180 offset:33792
	ds_read_b128 v[198:201], v180 offset:34816
	ds_read_b128 v[202:205], v180 offset:35840
	ds_read_b128 v[212:215], v180 offset:36864
	ds_read_b128 v[216:219], v180 offset:37888
	ds_read_b128 v[220:223], v180 offset:38912
	ds_read_b128 v[224:227], v180 offset:39936
	global_load_lds_dwordx4 v136, s[30:31]
	s_mov_b32 m0, s48
	s_nop 0
	global_load_lds_dwordx4 v140, s[30:31]
	s_waitcnt vmcnt(8)
	s_waitcnt lgkmcnt(0)
	s_barrier
	s_setprio 1
	s_waitcnt lgkmcnt(0)
	v_mfma_f32_16x16x32_bf16 v[124:127], v[128:131], v[190:193], v[124:127]
	v_mfma_f32_16x16x32_bf16 v[120:123], v[158:161], v[190:193], v[120:123]
	v_mfma_f32_16x16x32_bf16 v[108:111], v[128:131], v[198:201], v[108:111]
	v_mfma_f32_16x16x32_bf16 v[104:107], v[158:161], v[198:201], v[104:107]
	v_mfma_f32_16x16x32_bf16 v[92:95], v[128:131], v[212:215], v[92:95]
	v_mfma_f32_16x16x32_bf16 v[88:91], v[158:161], v[212:215], v[88:91]
	v_mfma_f32_16x16x32_bf16 v[76:79], v[128:131], v[220:223], v[76:79]
	v_mfma_f32_16x16x32_bf16 v[72:75], v[158:161], v[220:223], v[72:75]
	v_mfma_f32_16x16x32_bf16 v[124:127], v[132:135], v[194:197], v[124:127]
	v_mfma_f32_16x16x32_bf16 v[120:123], v[162:165], v[194:197], v[120:123]
	v_mfma_f32_16x16x32_bf16 v[108:111], v[132:135], v[202:205], v[108:111]
	v_mfma_f32_16x16x32_bf16 v[104:107], v[162:165], v[202:205], v[104:107]
	v_mfma_f32_16x16x32_bf16 v[92:95], v[132:135], v[216:219], v[92:95]
	v_mfma_f32_16x16x32_bf16 v[88:91], v[162:165], v[216:219], v[88:91]
	v_mfma_f32_16x16x32_bf16 v[76:79], v[132:135], v[224:227], v[76:79]
	v_mfma_f32_16x16x32_bf16 v[72:75], v[162:165], v[224:227], v[72:75]
	s_setprio 0
	s_setprio 1
	v_mfma_f32_16x16x32_bf16 v[116:119], v[166:169], v[190:193], v[116:119]
	v_mfma_f32_16x16x32_bf16 v[112:115], v[174:177], v[190:193], v[112:115]
	v_mfma_f32_16x16x32_bf16 v[100:103], v[166:169], v[198:201], v[100:103]
	v_mfma_f32_16x16x32_bf16 v[96:99], v[174:177], v[198:201], v[96:99]
	v_mfma_f32_16x16x32_bf16 v[84:87], v[166:169], v[212:215], v[84:87]
	v_mfma_f32_16x16x32_bf16 v[80:83], v[174:177], v[212:215], v[80:83]
	v_mfma_f32_16x16x32_bf16 v[68:71], v[166:169], v[220:223], v[68:71]
	v_mfma_f32_16x16x32_bf16 v[64:67], v[174:177], v[220:223], v[64:67]
	v_mfma_f32_16x16x32_bf16 v[116:119], v[170:173], v[194:197], v[116:119]
	v_mfma_f32_16x16x32_bf16 v[112:115], v[186:189], v[194:197], v[112:115]
	v_mfma_f32_16x16x32_bf16 v[100:103], v[170:173], v[202:205], v[100:103]
	v_mfma_f32_16x16x32_bf16 v[96:99], v[186:189], v[202:205], v[96:99]
	v_mfma_f32_16x16x32_bf16 v[84:87], v[170:173], v[216:219], v[84:87]
	v_mfma_f32_16x16x32_bf16 v[80:83], v[186:189], v[216:219], v[80:83]
	v_mfma_f32_16x16x32_bf16 v[68:71], v[170:173], v[224:227], v[68:71]
	v_mfma_f32_16x16x32_bf16 v[64:67], v[186:189], v[224:227], v[64:67]
	s_setprio 0
	s_barrier
	s_add_i32 s30, s33, s36
	s_mov_b32 m0, s30
	ds_read_b128 v[190:193], v180 offset:49152
	ds_read_b128 v[194:197], v180 offset:50176
	ds_read_b128 v[198:201], v180 offset:51200
	ds_read_b128 v[202:205], v180 offset:52224
	ds_read_b128 v[212:215], v180 offset:53248
	ds_read_b128 v[216:219], v180 offset:54272
	ds_read_b128 v[220:223], v180 offset:55296
	ds_read_b128 v[224:227], v180 offset:56320
	global_load_lds_dwordx4 v138, s[98:99]
	s_add_i32 m0, s30, 0x2000
	s_add_u32 s28, s28, 0x40080
	s_addc_u32 s29, s29, 0
	s_add_i32 s30, s69, s36
	global_load_lds_dwordx4 v142, s[98:99]
	s_mov_b32 m0, s30
	s_nop 0
	global_load_lds_dwordx4 v138, s[28:29]
	s_add_i32 m0, s30, 0x2000
	s_nop 0
	global_load_lds_dwordx4 v142, s[28:29]
	s_mov_b32 m0, s52
	s_nop 0
	global_load_lds_dwordx4 v136, s[100:101]
	s_mov_b32 m0, s53
	s_nop 0
	global_load_lds_dwordx4 v140, s[100:101]
	s_waitcnt vmcnt(8)
	s_waitcnt lgkmcnt(0)
	s_barrier
	s_setprio 1
	s_waitcnt lgkmcnt(0)
	v_mfma_f32_16x16x32_bf16 v[60:63], v[128:131], v[190:193], v[60:63]
	v_mfma_f32_16x16x32_bf16 v[56:59], v[158:161], v[190:193], v[56:59]
	v_mfma_f32_16x16x32_bf16 v[44:47], v[128:131], v[198:201], v[44:47]
	v_mfma_f32_16x16x32_bf16 v[40:43], v[158:161], v[198:201], v[40:43]
	v_mfma_f32_16x16x32_bf16 v[28:31], v[128:131], v[212:215], v[28:31]
	v_mfma_f32_16x16x32_bf16 v[24:27], v[158:161], v[212:215], v[24:27]
	v_mfma_f32_16x16x32_bf16 v[12:15], v[128:131], v[220:223], v[12:15]
	v_mfma_f32_16x16x32_bf16 v[8:11], v[158:161], v[220:223], v[8:11]
	v_mfma_f32_16x16x32_bf16 v[60:63], v[132:135], v[194:197], v[60:63]
	v_mfma_f32_16x16x32_bf16 v[56:59], v[162:165], v[194:197], v[56:59]
	v_mfma_f32_16x16x32_bf16 v[44:47], v[132:135], v[202:205], v[44:47]
	v_mfma_f32_16x16x32_bf16 v[40:43], v[162:165], v[202:205], v[40:43]
	v_mfma_f32_16x16x32_bf16 v[28:31], v[132:135], v[216:219], v[28:31]
	v_mfma_f32_16x16x32_bf16 v[24:27], v[162:165], v[216:219], v[24:27]
	v_mfma_f32_16x16x32_bf16 v[12:15], v[132:135], v[224:227], v[12:15]
	v_mfma_f32_16x16x32_bf16 v[8:11], v[162:165], v[224:227], v[8:11]
	s_setprio 0
	s_setprio 1
	v_mfma_f32_16x16x32_bf16 v[52:55], v[166:169], v[190:193], v[52:55]
	v_mfma_f32_16x16x32_bf16 v[48:51], v[174:177], v[190:193], v[48:51]
	v_mfma_f32_16x16x32_bf16 v[36:39], v[166:169], v[198:201], v[36:39]
	v_mfma_f32_16x16x32_bf16 v[32:35], v[174:177], v[198:201], v[32:35]
	v_mfma_f32_16x16x32_bf16 v[20:23], v[166:169], v[212:215], v[20:23]
	v_mfma_f32_16x16x32_bf16 v[16:19], v[174:177], v[212:215], v[16:19]
	v_mfma_f32_16x16x32_bf16 v[4:7], v[166:169], v[220:223], v[4:7]
	v_mfma_f32_16x16x32_bf16 v[0:3], v[174:177], v[220:223], v[0:3]
	v_mfma_f32_16x16x32_bf16 v[52:55], v[170:173], v[194:197], v[52:55]
	v_mfma_f32_16x16x32_bf16 v[48:51], v[186:189], v[194:197], v[48:51]
	v_mfma_f32_16x16x32_bf16 v[36:39], v[170:173], v[202:205], v[36:39]
	v_mfma_f32_16x16x32_bf16 v[32:35], v[186:189], v[202:205], v[32:35]
	v_mfma_f32_16x16x32_bf16 v[20:23], v[170:173], v[216:219], v[20:23]
	v_mfma_f32_16x16x32_bf16 v[16:19], v[186:189], v[216:219], v[16:19]
	v_mfma_f32_16x16x32_bf16 v[4:7], v[170:173], v[224:227], v[4:7]
	v_mfma_f32_16x16x32_bf16 v[0:3], v[186:189], v[224:227], v[0:3]
	s_setprio 0
	s_barrier
	s_add_i32 s68, s68, 2
	s_add_u32 s26, s26, 0x100
	s_addc_u32 s27, s27, 0
	s_add_u32 s19, s19, 0x100
	s_addc_u32 s21, s21, 0
	s_cmp_gt_u32 s68, 13
	s_cbranch_scc0 .LBB0_491
	s_and_b64 vcc, exec, s[14:15]
	s_cbranch_vccz .LBB0_494
	s_barrier

.LBB0_1046:
	s_ashr_i32 s19, s18, 31
	s_lshl_b64 s[20:21], s[18:19], 19
	s_add_u32 s20, s10, s20
	s_addc_u32 s21, s11, s21
	s_and_b64 s[22:23], s[4:5], exec
	s_cselect_b32 s19, s21, s27
	s_cselect_b32 s70, s20, s26
	s_ashr_i32 s17, s16, 31
	s_lshl_b64 s[22:23], s[16:17], 19
	s_add_u32 s22, s42, s22
	s_addc_u32 s23, s43, s23
	s_and_b64 s[34:35], s[4:5], exec
	s_cselect_b32 s17, s23, s31
	s_cselect_b32 s71, s22, s30
	s_cmp_lg_u32 s28, 0
	s_cselect_b64 s[28:29], -1, 0
	s_add_u32 s72, s30, 0x100
	v_mov_b64_e32 v[0:1], 0
	v_lshl_add_u64 v[146:147], s[26:27], 0, v[138:139]
	v_lshl_add_u64 v[148:149], s[26:27], 0, v[140:141]
	s_addc_u32 s73, s31, 0
	s_mov_b32 s74, -2
	s_mov_b64 s[30:31], 0
	v_mov_b64_e32 v[2:3], 0
	v_mov_b64_e32 v[4:5], 0
	v_mov_b64_e32 v[6:7], 0
	v_mov_b64_e32 v[16:17], 0
	v_mov_b64_e32 v[18:19], 0
	v_mov_b64_e32 v[20:21], 0
	v_mov_b64_e32 v[22:23], 0
	v_mov_b64_e32 v[32:33], 0
	v_mov_b64_e32 v[34:35], 0
	v_mov_b64_e32 v[36:37], 0
	v_mov_b64_e32 v[38:39], 0
	v_mov_b64_e32 v[48:49], 0
	v_mov_b64_e32 v[50:51], 0
	v_mov_b64_e32 v[52:53], 0
	v_mov_b64_e32 v[54:55], 0
	v_mov_b64_e32 v[8:9], 0
	v_mov_b64_e32 v[10:11], 0
	v_mov_b64_e32 v[12:13], 0
	v_mov_b64_e32 v[14:15], 0
	v_mov_b64_e32 v[24:25], 0
	v_mov_b64_e32 v[26:27], 0
	v_mov_b64_e32 v[28:29], 0
	v_mov_b64_e32 v[30:31], 0
	v_mov_b64_e32 v[40:41], 0
	v_mov_b64_e32 v[42:43], 0
	v_mov_b64_e32 v[44:45], 0
	v_mov_b64_e32 v[46:47], 0
	v_mov_b64_e32 v[56:57], 0
	v_mov_b64_e32 v[58:59], 0
	v_mov_b64_e32 v[60:61], 0
	v_mov_b64_e32 v[62:63], 0
	v_mov_b64_e32 v[64:65], 0
	v_mov_b64_e32 v[66:67], 0
	v_mov_b64_e32 v[68:69], 0
	v_mov_b64_e32 v[70:71], 0
	v_mov_b64_e32 v[80:81], 0
	v_mov_b64_e32 v[82:83], 0
	v_mov_b64_e32 v[84:85], 0
	v_mov_b64_e32 v[86:87], 0
	v_mov_b64_e32 v[96:97], 0
	v_mov_b64_e32 v[98:99], 0
	v_mov_b64_e32 v[100:101], 0
	v_mov_b64_e32 v[102:103], 0
	v_mov_b64_e32 v[112:113], 0
	v_mov_b64_e32 v[114:115], 0
	v_mov_b64_e32 v[116:117], 0
	v_mov_b64_e32 v[118:119], 0
	v_mov_b64_e32 v[72:73], 0
	v_mov_b64_e32 v[74:75], 0
	v_mov_b64_e32 v[76:77], 0
	v_mov_b64_e32 v[78:79], 0
	v_mov_b64_e32 v[88:89], 0
	v_mov_b64_e32 v[90:91], 0
	v_mov_b64_e32 v[92:93], 0
	v_mov_b64_e32 v[94:95], 0
	v_mov_b64_e32 v[104:105], 0
	v_mov_b64_e32 v[106:107], 0
	v_mov_b64_e32 v[108:109], 0
	v_mov_b64_e32 v[110:111], 0
	v_mov_b64_e32 v[120:121], 0
	v_mov_b64_e32 v[122:123], 0
	v_mov_b64_e32 v[124:125], 0
	v_mov_b64_e32 v[126:127], 0
	v_add_u32_e32 v253, 0x18000, v150
	v_add_u32_e32 v254, 0x1c000, v150
.LBB0_1047:
	s_add_u32 s98, s26, s30
	s_addc_u32 s99, s27, s31
	ds_read_b128 v[156:159], v152
	ds_read_b128 v[160:163], v152 offset:1024
	ds_read_b128 v[164:167], v152 offset:2048
	ds_read_b128 v[168:171], v152 offset:3072
	ds_read_b128 v[172:175], v153
	ds_read_b128 v[176:179], v153 offset:1024
	ds_read_b128 v[180:183], v153 offset:2048
	ds_read_b128 v[184:187], v153 offset:3072
	s_add_u32 s33, s26, s30
	s_addc_u32 s34, s27, s31
	s_add_u32 s33, s33, 0x100
	s_addc_u32 s36, s34, 0
	s_add_u32 s75, s72, s30
	s_addc_u32 s76, s73, s31
	s_cmp_eq_u32 s30, 0
	s_cselect_b64 s[34:35], -1, 0
	s_and_b64 s[34:35], s[28:29], s[34:35]
	s_cselect_b32 s32, 1, 0
	s_cmpk_eq_i32 s30, 0x700
	s_cselect_b32 s37, s19, s36
	s_cselect_b32 s36, s70, s33
	s_mov_b32 s33, s32
	s_cselect_b32 s35, s17, s76
	s_cselect_b32 s34, s71, s75
	s_add_i32 m0, s25, 0xc000
	ds_read_b128 v[188:191], v154
	ds_read_b128 v[192:195], v154 offset:1024
	ds_read_b128 v[196:199], v154 offset:2048
	ds_read_b128 v[200:203], v154 offset:3072
	ds_read_b128 v[204:207], v154 offset:4096
	ds_read_b128 v[212:215], v154 offset:5120
	ds_read_b128 v[216:219], v154 offset:6144
	ds_read_b128 v[220:223], v154 offset:7168
	global_load_lds_dwordx4 v138, s[98:99]
	s_add_i32 m0, s25, 0xe000
	s_and_b32 s33, s33, 1
	global_load_lds_dwordx4 v140, s[98:99]
	s_cmp_lg_u32 s33, 0
	s_cbranch_scc1 .Lpg8skip8
	s_waitcnt vmcnt(8)

.Lpg8skip9:
	s_waitcnt lgkmcnt(0)
	s_barrier
	s_setprio 1
	s_waitcnt lgkmcnt(0)
	v_mfma_f32_16x16x32_bf16 v[60:63], v[156:159], v[188:191], v[60:63]
	v_mfma_f32_16x16x32_bf16 v[56:59], v[164:167], v[188:191], v[56:59]
	v_mfma_f32_16x16x32_bf16 v[44:47], v[156:159], v[196:199], v[44:47]
	v_mfma_f32_16x16x32_bf16 v[40:43], v[164:167], v[196:199], v[40:43]
	v_mfma_f32_16x16x32_bf16 v[28:31], v[156:159], v[204:207], v[28:31]
	v_mfma_f32_16x16x32_bf16 v[24:27], v[164:167], v[204:207], v[24:27]
	v_mfma_f32_16x16x32_bf16 v[12:15], v[156:159], v[216:219], v[12:15]
	v_mfma_f32_16x16x32_bf16 v[8:11], v[164:167], v[216:219], v[8:11]
	v_mfma_f32_16x16x32_bf16 v[60:63], v[160:163], v[192:195], v[60:63]
	v_mfma_f32_16x16x32_bf16 v[56:59], v[168:171], v[192:195], v[56:59]
	v_mfma_f32_16x16x32_bf16 v[44:47], v[160:163], v[200:203], v[44:47]
	v_mfma_f32_16x16x32_bf16 v[40:43], v[168:171], v[200:203], v[40:43]
	v_mfma_f32_16x16x32_bf16 v[28:31], v[160:163], v[212:215], v[28:31]
	v_mfma_f32_16x16x32_bf16 v[24:27], v[168:171], v[212:215], v[24:27]
	v_mfma_f32_16x16x32_bf16 v[12:15], v[160:163], v[220:223], v[12:15]
	v_mfma_f32_16x16x32_bf16 v[8:11], v[168:171], v[220:223], v[8:11]
	s_setprio 0
	s_setprio 1
	v_mfma_f32_16x16x32_bf16 v[52:55], v[172:175], v[188:191], v[52:55]
	v_mfma_f32_16x16x32_bf16 v[48:51], v[180:183], v[188:191], v[48:51]
	v_mfma_f32_16x16x32_bf16 v[36:39], v[172:175], v[196:199], v[36:39]
	v_mfma_f32_16x16x32_bf16 v[32:35], v[180:183], v[196:199], v[32:35]
	v_mfma_f32_16x16x32_bf16 v[20:23], v[172:175], v[204:207], v[20:23]
	v_mfma_f32_16x16x32_bf16 v[16:19], v[180:183], v[204:207], v[16:19]
	v_mfma_f32_16x16x32_bf16 v[4:7], v[172:175], v[216:219], v[4:7]
	v_mfma_f32_16x16x32_bf16 v[0:3], v[180:183], v[216:219], v[0:3]
	v_mfma_f32_16x16x32_bf16 v[52:55], v[176:179], v[192:195], v[52:55]
	v_mfma_f32_16x16x32_bf16 v[48:51], v[184:187], v[192:195], v[48:51]
	v_mfma_f32_16x16x32_bf16 v[36:39], v[176:179], v[200:203], v[36:39]
	v_mfma_f32_16x16x32_bf16 v[32:35], v[184:187], v[200:203], v[32:35]
	v_mfma_f32_16x16x32_bf16 v[20:23], v[176:179], v[212:215], v[20:23]
	v_mfma_f32_16x16x32_bf16 v[16:19], v[184:187], v[212:215], v[16:19]
	v_mfma_f32_16x16x32_bf16 v[4:7], v[176:179], v[220:223], v[4:7]
	v_mfma_f32_16x16x32_bf16 v[0:3], v[184:187], v[220:223], v[0:3]
	s_setprio 0
	s_barrier
	s_add_i32 s33, 0, 0x18000
	s_add_i32 s75, 0, 0x1c000
	ds_read_b128 v[156:159], v253
	ds_read_b128 v[160:163], v253 offset:1024
	ds_read_b128 v[164:167], v253 offset:2048
	ds_read_b128 v[168:171], v253 offset:3072
	ds_read_b128 v[172:175], v254
	ds_read_b128 v[176:179], v254 offset:1024
	ds_read_b128 v[180:183], v254 offset:2048
	ds_read_b128 v[184:187], v254 offset:3072
	s_add_u32 s36, s36, 0x40000
	s_addc_u32 s37, s37, 0
	s_mov_b32 m0, s47
	ds_read_b128 v[188:191], v154 offset:32768
	ds_read_b128 v[192:195], v154 offset:33792
	ds_read_b128 v[196:199], v154 offset:34816
	ds_read_b128 v[200:203], v154 offset:35840
	ds_read_b128 v[204:207], v154 offset:36864
	ds_read_b128 v[212:215], v154 offset:37888
	ds_read_b128 v[216:219], v154 offset:38912
	ds_read_b128 v[220:223], v154 offset:39936
	global_load_lds_dwordx4 v134, s[36:37]
	s_mov_b32 m0, s48
	s_nop 0
	global_load_lds_dwordx4 v130, s[36:37]
	s_waitcnt vmcnt(8)
	s_waitcnt lgkmcnt(0)
	s_barrier
	s_setprio 1
	s_waitcnt lgkmcnt(0)
	v_mfma_f32_16x16x32_bf16 v[124:127], v[156:159], v[188:191], v[124:127]
	v_mfma_f32_16x16x32_bf16 v[120:123], v[164:167], v[188:191], v[120:123]
	v_mfma_f32_16x16x32_bf16 v[108:111], v[156:159], v[196:199], v[108:111]
	v_mfma_f32_16x16x32_bf16 v[104:107], v[164:167], v[196:199], v[104:107]
	v_mfma_f32_16x16x32_bf16 v[92:95], v[156:159], v[204:207], v[92:95]
	v_mfma_f32_16x16x32_bf16 v[88:91], v[164:167], v[204:207], v[88:91]
	v_mfma_f32_16x16x32_bf16 v[76:79], v[156:159], v[216:219], v[76:79]
	v_mfma_f32_16x16x32_bf16 v[72:75], v[164:167], v[216:219], v[72:75]
	v_mfma_f32_16x16x32_bf16 v[124:127], v[160:163], v[192:195], v[124:127]
	v_mfma_f32_16x16x32_bf16 v[120:123], v[168:171], v[192:195], v[120:123]
	v_mfma_f32_16x16x32_bf16 v[108:111], v[160:163], v[200:203], v[108:111]
	v_mfma_f32_16x16x32_bf16 v[104:107], v[168:171], v[200:203], v[104:107]
	v_mfma_f32_16x16x32_bf16 v[92:95], v[160:163], v[212:215], v[92:95]
	v_mfma_f32_16x16x32_bf16 v[88:91], v[168:171], v[212:215], v[88:91]
	v_mfma_f32_16x16x32_bf16 v[76:79], v[160:163], v[220:223], v[76:79]
	v_mfma_f32_16x16x32_bf16 v[72:75], v[168:171], v[220:223], v[72:75]
	s_setprio 0
	s_setprio 1
	v_mfma_f32_16x16x32_bf16 v[116:119], v[172:175], v[188:191], v[116:119]
	v_mfma_f32_16x16x32_bf16 v[112:115], v[180:183], v[188:191], v[112:115]
	v_mfma_f32_16x16x32_bf16 v[100:103], v[172:175], v[196:199], v[100:103]
	v_mfma_f32_16x16x32_bf16 v[96:99], v[180:183], v[196:199], v[96:99]
	v_mfma_f32_16x16x32_bf16 v[84:87], v[172:175], v[204:207], v[84:87]
	v_mfma_f32_16x16x32_bf16 v[80:83], v[180:183], v[204:207], v[80:83]
	v_mfma_f32_16x16x32_bf16 v[68:71], v[172:175], v[216:219], v[68:71]
	v_mfma_f32_16x16x32_bf16 v[64:67], v[180:183], v[216:219], v[64:67]
	v_mfma_f32_16x16x32_bf16 v[116:119], v[176:179], v[192:195], v[116:119]
	v_mfma_f32_16x16x32_bf16 v[112:115], v[184:187], v[192:195], v[112:115]
	v_mfma_f32_16x16x32_bf16 v[100:103], v[176:179], v[200:203], v[100:103]
	v_mfma_f32_16x16x32_bf16 v[96:99], v[184:187], v[200:203], v[96:99]
	v_mfma_f32_16x16x32_bf16 v[84:87], v[176:179], v[212:215], v[84:87]
	v_mfma_f32_16x16x32_bf16 v[80:83], v[184:187], v[212:215], v[80:83]
	v_mfma_f32_16x16x32_bf16 v[68:71], v[176:179], v[220:223], v[68:71]
	v_mfma_f32_16x16x32_bf16 v[64:67], v[184:187], v[220:223], v[64:67]
	s_setprio 0
	s_barrier
	s_add_i32 s33, s33, s44
	s_mov_b32 m0, s33
	ds_read_b128 v[188:191], v154 offset:49152
	ds_read_b128 v[192:195], v154 offset:50176
	ds_read_b128 v[196:199], v154 offset:51200
	ds_read_b128 v[200:203], v154 offset:52224
	ds_read_b128 v[204:207], v154 offset:53248
	ds_read_b128 v[212:215], v154 offset:54272
	ds_read_b128 v[216:219], v154 offset:55296
	ds_read_b128 v[220:223], v154 offset:56320
	global_load_lds_dwordx4 v132, s[98:99]
	s_add_i32 m0, s33, 0x2000
	s_add_u32 s34, s34, 0x40080
	s_addc_u32 s35, s35, 0
	s_add_i32 s33, s75, s44
	global_load_lds_dwordx4 v128, s[98:99]
	s_mov_b32 m0, s33
	s_nop 0
	global_load_lds_dwordx4 v132, s[34:35]
	s_add_i32 m0, s33, 0x2000
	s_nop 0
	global_load_lds_dwordx4 v128, s[34:35]
	s_mov_b32 m0, s50
	s_nop 0
	global_load_lds_dwordx4 v134, s[100:101]
	s_mov_b32 m0, s51
	s_nop 0
	global_load_lds_dwordx4 v130, s[100:101]
	s_waitcnt vmcnt(8)
	s_waitcnt lgkmcnt(0)
	s_barrier
	s_setprio 1
	s_waitcnt lgkmcnt(0)
	v_mfma_f32_16x16x32_bf16 v[60:63], v[156:159], v[188:191], v[60:63]
	v_mfma_f32_16x16x32_bf16 v[56:59], v[164:167], v[188:191], v[56:59]
	v_mfma_f32_16x16x32_bf16 v[44:47], v[156:159], v[196:199], v[44:47]
	v_mfma_f32_16x16x32_bf16 v[40:43], v[164:167], v[196:199], v[40:43]
	v_mfma_f32_16x16x32_bf16 v[28:31], v[156:159], v[204:207], v[28:31]
	v_mfma_f32_16x16x32_bf16 v[24:27], v[164:167], v[204:207], v[24:27]
	v_mfma_f32_16x16x32_bf16 v[12:15], v[156:159], v[216:219], v[12:15]
	v_mfma_f32_16x16x32_bf16 v[8:11], v[164:167], v[216:219], v[8:11]
	v_mfma_f32_16x16x32_bf16 v[60:63], v[160:163], v[192:195], v[60:63]
	v_mfma_f32_16x16x32_bf16 v[56:59], v[168:171], v[192:195], v[56:59]
	v_mfma_f32_16x16x32_bf16 v[44:47], v[160:163], v[200:203], v[44:47]
	v_mfma_f32_16x16x32_bf16 v[40:43], v[168:171], v[200:203], v[40:43]
	v_mfma_f32_16x16x32_bf16 v[28:31], v[160:163], v[212:215], v[28:31]
	v_mfma_f32_16x16x32_bf16 v[24:27], v[168:171], v[212:215], v[24:27]
	v_mfma_f32_16x16x32_bf16 v[12:15], v[160:163], v[220:223], v[12:15]
	v_mfma_f32_16x16x32_bf16 v[8:11], v[168:171], v[220:223], v[8:11]
	s_setprio 0
	s_setprio 1
	v_mfma_f32_16x16x32_bf16 v[52:55], v[172:175], v[188:191], v[52:55]
	v_mfma_f32_16x16x32_bf16 v[48:51], v[180:183], v[188:191], v[48:51]
	v_mfma_f32_16x16x32_bf16 v[36:39], v[172:175], v[196:199], v[36:39]
	v_mfma_f32_16x16x32_bf16 v[32:35], v[180:183], v[196:199], v[32:35]
	v_mfma_f32_16x16x32_bf16 v[20:23], v[172:175], v[204:207], v[20:23]
	v_mfma_f32_16x16x32_bf16 v[16:19], v[180:183], v[204:207], v[16:19]
	v_mfma_f32_16x16x32_bf16 v[4:7], v[172:175], v[216:219], v[4:7]
	v_mfma_f32_16x16x32_bf16 v[0:3], v[180:183], v[216:219], v[0:3]
	v_mfma_f32_16x16x32_bf16 v[52:55], v[176:179], v[192:195], v[52:55]
	v_mfma_f32_16x16x32_bf16 v[48:51], v[184:187], v[192:195], v[48:51]
	v_mfma_f32_16x16x32_bf16 v[36:39], v[176:179], v[200:203], v[36:39]
	v_mfma_f32_16x16x32_bf16 v[32:35], v[184:187], v[200:203], v[32:35]
	v_mfma_f32_16x16x32_bf16 v[20:23], v[176:179], v[212:215], v[20:23]
	v_mfma_f32_16x16x32_bf16 v[16:19], v[184:187], v[212:215], v[16:19]
	v_mfma_f32_16x16x32_bf16 v[4:7], v[176:179], v[220:223], v[4:7]
	v_mfma_f32_16x16x32_bf16 v[0:3], v[184:187], v[220:223], v[0:3]
	s_setprio 0
	s_barrier
	s_add_i32 s74, s74, 2
	s_add_u32 s30, s30, 0x100
	s_addc_u32 s31, s31, 0
	s_cmp_gt_u32 s74, 13
	s_cbranch_scc0 .LBB0_1047
	s_and_b64 vcc, exec, s[14:15]
	s_cbranch_vccz .LBB0_1050
	s_barrier

.LBB0_1123:
	s_add_u32 s50, s20, 0x100
	v_mov_b64_e32 v[0:1], 0
	s_addc_u32 s51, s21, 0
	s_mov_b32 s52, -2
	v_mov_b64_e32 v[2:3], 0
	v_mov_b64_e32 v[4:5], 0
	v_mov_b64_e32 v[6:7], 0
	v_mov_b64_e32 v[8:9], 0
	v_mov_b64_e32 v[10:11], 0
	v_mov_b64_e32 v[20:21], 0
	v_mov_b64_e32 v[22:23], 0
	v_mov_b64_e32 v[24:25], 0
	v_mov_b64_e32 v[26:27], 0
	v_mov_b64_e32 v[36:37], 0
	v_mov_b64_e32 v[38:39], 0
	v_mov_b64_e32 v[40:41], 0
	v_mov_b64_e32 v[42:43], 0
	v_mov_b64_e32 v[52:53], 0
	v_mov_b64_e32 v[54:55], 0
	v_mov_b64_e32 v[12:13], 0
	v_mov_b64_e32 v[14:15], 0
	v_mov_b64_e32 v[16:17], 0
	v_mov_b64_e32 v[18:19], 0
	v_mov_b64_e32 v[28:29], 0
	v_mov_b64_e32 v[30:31], 0
	v_mov_b64_e32 v[32:33], 0
	v_mov_b64_e32 v[34:35], 0
	v_mov_b64_e32 v[44:45], 0
	v_mov_b64_e32 v[46:47], 0
	v_mov_b64_e32 v[48:49], 0
	v_mov_b64_e32 v[50:51], 0
	v_mov_b64_e32 v[56:57], 0
	v_mov_b64_e32 v[58:59], 0
	v_mov_b64_e32 v[60:61], 0
	v_mov_b64_e32 v[62:63], 0
	v_mov_b64_e32 v[64:65], 0
	v_mov_b64_e32 v[66:67], 0
	v_mov_b64_e32 v[68:69], 0
	v_mov_b64_e32 v[70:71], 0
	v_mov_b64_e32 v[72:73], 0
	v_mov_b64_e32 v[74:75], 0
	v_mov_b64_e32 v[84:85], 0
	v_mov_b64_e32 v[86:87], 0
	v_mov_b64_e32 v[88:89], 0
	v_mov_b64_e32 v[90:91], 0
	v_mov_b64_e32 v[100:101], 0
	v_mov_b64_e32 v[102:103], 0
	v_mov_b64_e32 v[104:105], 0
	v_mov_b64_e32 v[106:107], 0
	v_mov_b64_e32 v[116:117], 0
	v_mov_b64_e32 v[118:119], 0
	v_mov_b64_e32 v[76:77], 0
	v_mov_b64_e32 v[78:79], 0
	v_mov_b64_e32 v[80:81], 0
	v_mov_b64_e32 v[82:83], 0
	v_mov_b64_e32 v[92:93], 0
	v_mov_b64_e32 v[94:95], 0
	v_mov_b64_e32 v[96:97], 0
	v_mov_b64_e32 v[98:99], 0
	v_mov_b64_e32 v[108:109], 0
	v_mov_b64_e32 v[110:111], 0
	v_mov_b64_e32 v[112:113], 0
	v_mov_b64_e32 v[114:115], 0
	v_mov_b64_e32 v[120:121], 0
	v_mov_b64_e32 v[122:123], 0
	v_mov_b64_e32 v[124:125], 0
	v_mov_b64_e32 v[126:127], 0
	v_add_u32_e32 v253, 0x18000, v153
	v_add_u32_e32 v254, 0x1c000, v153

.Lpg8skip11:
	s_waitcnt lgkmcnt(0)
	s_barrier
	s_setprio 1
	s_waitcnt lgkmcnt(0)
	v_mfma_f32_16x16x32_bf16 v[60:63], v[144:147], v[182:185], v[60:63]
	v_mfma_f32_16x16x32_bf16 v[56:59], v[158:161], v[182:185], v[56:59]
	v_mfma_f32_16x16x32_bf16 v[48:51], v[144:147], v[190:193], v[48:51]
	v_mfma_f32_16x16x32_bf16 v[44:47], v[158:161], v[190:193], v[44:47]
	v_mfma_f32_16x16x32_bf16 v[32:35], v[144:147], v[198:201], v[32:35]
	v_mfma_f32_16x16x32_bf16 v[28:31], v[158:161], v[198:201], v[28:31]
	v_mfma_f32_16x16x32_bf16 v[16:19], v[144:147], v[206:209], v[16:19]
	v_mfma_f32_16x16x32_bf16 v[12:15], v[158:161], v[206:209], v[12:15]
	v_mfma_f32_16x16x32_bf16 v[60:63], v[148:151], v[186:189], v[60:63]
	v_mfma_f32_16x16x32_bf16 v[56:59], v[162:165], v[186:189], v[56:59]
	v_mfma_f32_16x16x32_bf16 v[48:51], v[148:151], v[194:197], v[48:51]
	v_mfma_f32_16x16x32_bf16 v[44:47], v[162:165], v[194:197], v[44:47]
	v_mfma_f32_16x16x32_bf16 v[32:35], v[148:151], v[202:205], v[32:35]
	v_mfma_f32_16x16x32_bf16 v[28:31], v[162:165], v[202:205], v[28:31]
	v_mfma_f32_16x16x32_bf16 v[16:19], v[148:151], v[210:213], v[16:19]
	v_mfma_f32_16x16x32_bf16 v[12:15], v[162:165], v[210:213], v[12:15]
	s_setprio 0
	s_setprio 1
	v_mfma_f32_16x16x32_bf16 v[52:55], v[166:169], v[182:185], v[52:55]
	v_mfma_f32_16x16x32_bf16 v[40:43], v[174:177], v[182:185], v[40:43]
	v_mfma_f32_16x16x32_bf16 v[36:39], v[166:169], v[190:193], v[36:39]
	v_mfma_f32_16x16x32_bf16 v[24:27], v[174:177], v[190:193], v[24:27]
	v_mfma_f32_16x16x32_bf16 v[20:23], v[166:169], v[198:201], v[20:23]
	v_mfma_f32_16x16x32_bf16 v[8:11], v[174:177], v[198:201], v[8:11]
	v_mfma_f32_16x16x32_bf16 v[4:7], v[166:169], v[206:209], v[4:7]
	v_mfma_f32_16x16x32_bf16 v[0:3], v[174:177], v[206:209], v[0:3]
	v_mfma_f32_16x16x32_bf16 v[52:55], v[170:173], v[186:189], v[52:55]
	v_mfma_f32_16x16x32_bf16 v[40:43], v[178:181], v[186:189], v[40:43]
	v_mfma_f32_16x16x32_bf16 v[36:39], v[170:173], v[194:197], v[36:39]
	v_mfma_f32_16x16x32_bf16 v[24:27], v[178:181], v[194:197], v[24:27]
	v_mfma_f32_16x16x32_bf16 v[20:23], v[170:173], v[202:205], v[20:23]
	v_mfma_f32_16x16x32_bf16 v[8:11], v[178:181], v[202:205], v[8:11]
	v_mfma_f32_16x16x32_bf16 v[4:7], v[170:173], v[210:213], v[4:7]
	v_mfma_f32_16x16x32_bf16 v[0:3], v[178:181], v[210:213], v[0:3]
	s_setprio 0
	s_barrier
	s_add_i32 s53, 0, 0x18000
	s_add_i32 s54, 0, 0x1c000
	ds_read_b128 v[144:147], v253
	ds_read_b128 v[148:151], v253 offset:1024
	ds_read_b128 v[158:161], v253 offset:2048
	ds_read_b128 v[162:165], v253 offset:3072
	ds_read_b128 v[166:169], v254
	ds_read_b128 v[170:173], v254 offset:1024
	ds_read_b128 v[174:177], v254 offset:2048
	ds_read_b128 v[178:181], v254 offset:3072
	s_add_u32 s18, s24, 0xb0000
	s_addc_u32 s19, s25, 0
	s_mov_b32 m0, s31
	ds_read_b128 v[182:185], v157 offset:32768
	ds_read_b128 v[186:189], v157 offset:33792
	ds_read_b128 v[190:193], v157 offset:34816
	ds_read_b128 v[194:197], v157 offset:35840
	ds_read_b128 v[198:201], v157 offset:36864
	ds_read_b128 v[202:205], v157 offset:37888
	ds_read_b128 v[206:209], v157 offset:38912
	ds_read_b128 v[210:213], v157 offset:39936
	global_load_lds_dwordx4 v134, s[18:19]
	s_mov_b32 m0, s33
	s_nop 0
	global_load_lds_dwordx4 v130, s[18:19]
	s_waitcnt vmcnt(8)
	s_waitcnt lgkmcnt(0)
	s_barrier
	s_setprio 1
	s_waitcnt lgkmcnt(0)
	v_mfma_f32_16x16x32_bf16 v[124:127], v[144:147], v[182:185], v[124:127]
	v_mfma_f32_16x16x32_bf16 v[120:123], v[158:161], v[182:185], v[120:123]
	v_mfma_f32_16x16x32_bf16 v[112:115], v[144:147], v[190:193], v[112:115]
	v_mfma_f32_16x16x32_bf16 v[108:111], v[158:161], v[190:193], v[108:111]
	v_mfma_f32_16x16x32_bf16 v[96:99], v[144:147], v[198:201], v[96:99]
	v_mfma_f32_16x16x32_bf16 v[92:95], v[158:161], v[198:201], v[92:95]
	v_mfma_f32_16x16x32_bf16 v[80:83], v[144:147], v[206:209], v[80:83]
	v_mfma_f32_16x16x32_bf16 v[76:79], v[158:161], v[206:209], v[76:79]
	v_mfma_f32_16x16x32_bf16 v[124:127], v[148:151], v[186:189], v[124:127]
	v_mfma_f32_16x16x32_bf16 v[120:123], v[162:165], v[186:189], v[120:123]
	v_mfma_f32_16x16x32_bf16 v[112:115], v[148:151], v[194:197], v[112:115]
	v_mfma_f32_16x16x32_bf16 v[108:111], v[162:165], v[194:197], v[108:111]
	v_mfma_f32_16x16x32_bf16 v[96:99], v[148:151], v[202:205], v[96:99]
	v_mfma_f32_16x16x32_bf16 v[92:95], v[162:165], v[202:205], v[92:95]
	v_mfma_f32_16x16x32_bf16 v[80:83], v[148:151], v[210:213], v[80:83]
	v_mfma_f32_16x16x32_bf16 v[76:79], v[162:165], v[210:213], v[76:79]
	s_setprio 0
	s_setprio 1
	v_mfma_f32_16x16x32_bf16 v[116:119], v[166:169], v[182:185], v[116:119]
	v_mfma_f32_16x16x32_bf16 v[104:107], v[174:177], v[182:185], v[104:107]
	v_mfma_f32_16x16x32_bf16 v[100:103], v[166:169], v[190:193], v[100:103]
	v_mfma_f32_16x16x32_bf16 v[88:91], v[174:177], v[190:193], v[88:91]
	v_mfma_f32_16x16x32_bf16 v[84:87], v[166:169], v[198:201], v[84:87]
	v_mfma_f32_16x16x32_bf16 v[72:75], v[174:177], v[198:201], v[72:75]
	v_mfma_f32_16x16x32_bf16 v[68:71], v[166:169], v[206:209], v[68:71]
	v_mfma_f32_16x16x32_bf16 v[64:67], v[174:177], v[206:209], v[64:67]
	v_mfma_f32_16x16x32_bf16 v[116:119], v[170:173], v[186:189], v[116:119]
	v_mfma_f32_16x16x32_bf16 v[104:107], v[178:181], v[186:189], v[104:107]
	v_mfma_f32_16x16x32_bf16 v[100:103], v[170:173], v[194:197], v[100:103]
	v_mfma_f32_16x16x32_bf16 v[88:91], v[178:181], v[194:197], v[88:91]
	v_mfma_f32_16x16x32_bf16 v[84:87], v[170:173], v[202:205], v[84:87]
	v_mfma_f32_16x16x32_bf16 v[72:75], v[178:181], v[202:205], v[72:75]
	v_mfma_f32_16x16x32_bf16 v[68:71], v[170:173], v[210:213], v[68:71]
	v_mfma_f32_16x16x32_bf16 v[64:67], v[178:181], v[210:213], v[64:67]
	s_setprio 0
	s_barrier
	s_add_i32 s18, s53, s28
	s_mov_b32 m0, s18
	ds_read_b128 v[182:185], v157 offset:49152
	ds_read_b128 v[186:189], v157 offset:50176
	ds_read_b128 v[190:193], v157 offset:51200
	ds_read_b128 v[194:197], v157 offset:52224
	ds_read_b128 v[198:201], v157 offset:53248
	ds_read_b128 v[202:205], v157 offset:54272
	ds_read_b128 v[206:209], v157 offset:55296
	ds_read_b128 v[210:213], v157 offset:56320
	global_load_lds_dwordx4 v132, s[98:99]
	s_add_i32 m0, s18, 0x2000
	s_add_u32 s18, s22, 0xb0080
	s_addc_u32 s19, s23, 0
	s_add_i32 s22, s54, s28
	global_load_lds_dwordx4 v128, s[98:99]
	s_mov_b32 m0, s22
	s_nop 0
	global_load_lds_dwordx4 v132, s[18:19]
	s_add_i32 m0, s22, 0x2000
	s_nop 0
	global_load_lds_dwordx4 v128, s[18:19]
	s_mov_b32 m0, s37
	s_nop 0
	global_load_lds_dwordx4 v134, s[100:101]
	s_mov_b32 m0, s38
	s_nop 0
	global_load_lds_dwordx4 v130, s[100:101]
	s_waitcnt vmcnt(8)
	s_waitcnt lgkmcnt(0)
	s_barrier
	s_setprio 1
	s_waitcnt lgkmcnt(0)
	v_mfma_f32_16x16x32_bf16 v[60:63], v[144:147], v[182:185], v[60:63]
	v_mfma_f32_16x16x32_bf16 v[56:59], v[158:161], v[182:185], v[56:59]
	v_mfma_f32_16x16x32_bf16 v[48:51], v[144:147], v[190:193], v[48:51]
	v_mfma_f32_16x16x32_bf16 v[44:47], v[158:161], v[190:193], v[44:47]
	v_mfma_f32_16x16x32_bf16 v[32:35], v[144:147], v[198:201], v[32:35]
	v_mfma_f32_16x16x32_bf16 v[28:31], v[158:161], v[198:201], v[28:31]
	v_mfma_f32_16x16x32_bf16 v[16:19], v[144:147], v[206:209], v[16:19]
	v_mfma_f32_16x16x32_bf16 v[12:15], v[158:161], v[206:209], v[12:15]
	v_mfma_f32_16x16x32_bf16 v[60:63], v[148:151], v[186:189], v[60:63]
	v_mfma_f32_16x16x32_bf16 v[56:59], v[162:165], v[186:189], v[56:59]
	v_mfma_f32_16x16x32_bf16 v[48:51], v[148:151], v[194:197], v[48:51]
	v_mfma_f32_16x16x32_bf16 v[44:47], v[162:165], v[194:197], v[44:47]
	v_mfma_f32_16x16x32_bf16 v[32:35], v[148:151], v[202:205], v[32:35]
	v_mfma_f32_16x16x32_bf16 v[28:31], v[162:165], v[202:205], v[28:31]
	v_mfma_f32_16x16x32_bf16 v[16:19], v[148:151], v[210:213], v[16:19]
	v_mfma_f32_16x16x32_bf16 v[12:15], v[162:165], v[210:213], v[12:15]
	s_setprio 0
	s_setprio 1
	v_mfma_f32_16x16x32_bf16 v[52:55], v[166:169], v[182:185], v[52:55]
	v_mfma_f32_16x16x32_bf16 v[40:43], v[174:177], v[182:185], v[40:43]
	v_mfma_f32_16x16x32_bf16 v[36:39], v[166:169], v[190:193], v[36:39]
	v_mfma_f32_16x16x32_bf16 v[24:27], v[174:177], v[190:193], v[24:27]
	v_mfma_f32_16x16x32_bf16 v[20:23], v[166:169], v[198:201], v[20:23]
	v_mfma_f32_16x16x32_bf16 v[8:11], v[174:177], v[198:201], v[8:11]
	v_mfma_f32_16x16x32_bf16 v[4:7], v[166:169], v[206:209], v[4:7]
	v_mfma_f32_16x16x32_bf16 v[0:3], v[174:177], v[206:209], v[0:3]
	v_mfma_f32_16x16x32_bf16 v[52:55], v[170:173], v[186:189], v[52:55]
	v_mfma_f32_16x16x32_bf16 v[40:43], v[178:181], v[186:189], v[40:43]
	v_mfma_f32_16x16x32_bf16 v[36:39], v[170:173], v[194:197], v[36:39]
	v_mfma_f32_16x16x32_bf16 v[24:27], v[178:181], v[194:197], v[24:27]
	v_mfma_f32_16x16x32_bf16 v[20:23], v[170:173], v[202:205], v[20:23]
	v_mfma_f32_16x16x32_bf16 v[8:11], v[178:181], v[202:205], v[8:11]
	v_mfma_f32_16x16x32_bf16 v[4:7], v[170:173], v[210:213], v[4:7]
	v_mfma_f32_16x16x32_bf16 v[0:3], v[178:181], v[210:213], v[0:3]
	s_setprio 0
	s_barrier
	s_add_i32 s52, s52, 2
	s_add_u32 s50, s50, 0x100
	s_addc_u32 s51, s51, 0
	s_cmp_gt_u32 s52, 41
	s_mov_b64 s[18:19], s[20:21]
	s_cbranch_scc0 .LBB0_1124
	s_and_b64 vcc, exec, s[14:15]
	s_cbranch_vccz .LBB0_1127
	s_barrier

	.amdhsa_kernel _Z8fwd_mega4Args
		.amdhsa_group_segment_fixed_size 0
		.amdhsa_private_segment_fixed_size 0
		.amdhsa_kernarg_size 432
		.amdhsa_user_sgpr_count 2
		.amdhsa_user_sgpr_dispatch_ptr 0
		.amdhsa_user_sgpr_queue_ptr 0
		.amdhsa_user_sgpr_kernarg_segment_ptr 1
		.amdhsa_user_sgpr_dispatch_id 0
		.amdhsa_user_sgpr_kernarg_preload_length 0
		.amdhsa_user_sgpr_kernarg_preload_offset 0
		.amdhsa_user_sgpr_private_segment_size 0
		.amdhsa_uses_dynamic_stack 0
		.amdhsa_enable_private_segment 0
		.amdhsa_system_sgpr_workgroup_id_x 1
		.amdhsa_system_sgpr_workgroup_id_y 0
		.amdhsa_system_sgpr_workgroup_id_z 0
		.amdhsa_system_sgpr_workgroup_info 0
		.amdhsa_system_vgpr_workitem_id 2
		.amdhsa_next_free_vgpr 255
		.amdhsa_next_free_sgpr 102
		.amdhsa_accum_offset 256
		.amdhsa_reserve_vcc 1
		.amdhsa_float_round_mode_32 0
		.amdhsa_float_round_mode_16_64 0
		.amdhsa_float_denorm_mode_32 3
		.amdhsa_float_denorm_mode_16_64 3
		.amdhsa_dx10_clamp 1
		.amdhsa_ieee_mode 1
		.amdhsa_fp16_overflow 0
		.amdhsa_tg_split 0
		.amdhsa_exception_fp_ieee_invalid_op 0
		.amdhsa_exception_fp_denorm_src 0
		.amdhsa_exception_fp_ieee_div_zero 0
		.amdhsa_exception_fp_ieee_overflow 0
		.amdhsa_exception_fp_ieee_underflow 0
		.amdhsa_exception_fp_ieee_inexact 0
		.amdhsa_exception_int_div_zero 0
	.end_amdhsa_kernel

.Lfunc_end0:
	.size	_Z8fwd_mega4Args, .Lfunc_end0-_Z8fwd_mega4Args
	.set _Z8fwd_mega4Args.num_vgpr, 255
	.set _Z8fwd_mega4Args.num_agpr, 0
	.set _Z8fwd_mega4Args.numbered_sgpr, 102
	.set _Z8fwd_mega4Args.num_named_barrier, 0
	.set _Z8fwd_mega4Args.private_seg_size, 0
	.set _Z8fwd_mega4Args.uses_vcc, 1
	.set _Z8fwd_mega4Args.uses_flat_scratch, 0
	.set _Z8fwd_mega4Args.has_dyn_sized_stack, 0
	.set _Z8fwd_mega4Args.has_recursion, 0
	.set _Z8fwd_mega4Args.has_indirect_call, 0

amdhsa.kernels:
  - .agpr_count:     0
    .args:
      - .offset:         0
        .size:           176
        .value_kind:     by_value
      - .offset:         176
        .size:           4
        .value_kind:     hidden_block_count_x
      - .offset:         180
        .size:           4
        .value_kind:     hidden_block_count_y
      - .offset:         184
        .size:           4
        .value_kind:     hidden_block_count_z
      - .offset:         188
        .size:           2
        .value_kind:     hidden_group_size_x
      - .offset:         190
        .size:           2
        .value_kind:     hidden_group_size_y
      - .offset:         192
        .size:           2
        .value_kind:     hidden_group_size_z
      - .offset:         194
        .size:           2
        .value_kind:     hidden_remainder_x
      - .offset:         196
        .size:           2
        .value_kind:     hidden_remainder_y
      - .offset:         198
        .size:           2
        .value_kind:     hidden_remainder_z
      - .offset:         216
        .size:           8
        .value_kind:     hidden_global_offset_x
      - .offset:         224
        .size:           8
        .value_kind:     hidden_global_offset_y
      - .offset:         232
        .size:           8
        .value_kind:     hidden_global_offset_z
      - .offset:         240
        .size:           2
        .value_kind:     hidden_grid_dims
      - .offset:         264
        .size:           8
        .value_kind:     hidden_multigrid_sync_arg
      - .offset:         296
        .size:           4
        .value_kind:     hidden_dynamic_lds_size
    .group_segment_fixed_size: 0
    .kernarg_segment_align: 8
    .kernarg_segment_size: 432
    .language:       OpenCL C
    .language_version:
      - 2
      - 0
    .max_flat_workgroup_size: 512
    .name:           _Z8fwd_mega4Args
    .private_segment_fixed_size: 0
    .sgpr_count:     108
    .sgpr_spill_count: 10
    .symbol:         _Z8fwd_mega4Args.kd
    .uniform_work_group_size: 1
    .uses_dynamic_stack: false
    .vgpr_count:     255
    .vgpr_spill_count: 0
    .wavefront_size: 64
